# adds v_rsq for the two per-row rstd statistics in prep_even (P3)
# speedup vs baseline: 1.0005x; 1.0005x over previous
; __device__ __forceinline__ float wave_sum_fast(float x) { x = reduce16(x); return (rl_(x, 0) + rl_(x, 16)) + (rl_(x, 32) + rl_(x, 48)); }
; __device__ __forceinline__ void prep_even_phase(const Ctx& F) {
;     ...
;             sq = wave_sum_fast(sq); skv = wave_sum_fast(skv) * 0.5f;
;             if (lane == 0) { stats[2 * row] = 1.0f / sqrtf(sq * (1.0f / 384.f) + 1e-6f); stats[2 * row + 1] = 1.0f / sqrtf(skv * (1.0f / 256.f) + 1e-6f); }
.LBB0_321:
	v_mov_b32_e32 v66, s21
	v_mov_b32_e32 v67, s42
	v_pk_add_f32 v[66:67], s[38:39], v[66:67]
	v_mov_b32_e32 v64, s56
	v_add_f32_e32 v66, v66, v67
	v_fmamk_f32 v66, v66, 0x3b2aaaab, v84
	v_rsq_f32_e32 v140, v66
	v_mov_b32_e32 v65, s57
	v_pk_add_f32 v[64:65], s[16:17], v[64:65]
	v_add_f32_e32 v64, v64, v65
	v_mul_f32_e32 v64, 0.5, v64
	v_fmamk_f32 v64, v64, 0x3b800000, v84
	s_ashr_i32 s21, s20, 31
	s_lshl_b64 s[16:17], s[20:21], 2
	s_add_u32 s38, s1, s16
	v_rsq_f32_e32 v141, v64
	s_addc_u32 s39, s3, s17
	s_nop 0
	v_mov_b32_e32 v64, v140
	v_mov_b32_e32 v65, v141
	global_store_dwordx2 v75, v[64:65], s[38:39]
	s_or_b64 exec, exec, s[36:37]
	s_and_saveexec_b64 s[16:17], s[8:9]
	s_cbranch_execz .LBB0_320

; __device__ __forceinline__ float wave_sum_fast(float x) { x = reduce16(x); return (rl_(x, 0) + rl_(x, 16)) + (rl_(x, 32) + rl_(x, 48)); }
; __device__ __forceinline__ void prep_even_phase(const Ctx& F) {
;     ...
;             sq = wave_sum_fast(sq); skv = wave_sum_fast(skv) * 0.5f;
;             if (lane == 0) { stats[2 * row] = 1.0f / sqrtf(sq * (1.0f / 384.f) + 1e-6f); stats[2 * row + 1] = 1.0f / sqrtf(skv * (1.0f / 256.f) + 1e-6f); }
.LBB0_391:
	v_mov_b32_e32 v50, s21
	v_mov_b32_e32 v51, s23
	v_pk_add_f32 v[50:51], s[38:39], v[50:51]
	v_mov_b32_e32 v48, s42
	v_add_f32_e32 v50, v50, v51
	v_fmamk_f32 v50, v50, 0x3b2aaaab, v84
	v_rsq_f32_e32 v142, v50
	v_mov_b32_e32 v49, s56
	v_pk_add_f32 v[48:49], s[16:17], v[48:49]
	v_add_f32_e32 v48, v48, v49
	v_mul_f32_e32 v48, 0.5, v48
	v_fmamk_f32 v48, v48, 0x3b800000, v84
	s_add_i32 s16, s20, 2
	s_ashr_i32 s17, s16, 31
	v_rsq_f32_e32 v143, v48
	s_lshl_b64 s[16:17], s[16:17], 2
	s_add_u32 s38, s1, s16
	s_addc_u32 s39, s3, s17
	v_mov_b32_e32 v48, v142
	v_mov_b32_e32 v49, v143
	global_store_dwordx2 v75, v[48:49], s[38:39]
	s_or_b64 exec, exec, s[36:37]
	s_and_saveexec_b64 s[16:17], s[8:9]
	s_cbranch_execz .LBB0_390

; __device__ __forceinline__ float wave_sum_fast(float x) { x = reduce16(x); return (rl_(x, 0) + rl_(x, 16)) + (rl_(x, 32) + rl_(x, 48)); }
; __device__ __forceinline__ void prep_even_phase(const Ctx& F) {
;     ...
;             sq = wave_sum_fast(sq); skv = wave_sum_fast(skv) * 0.5f;
;             if (lane == 0) { stats[2 * row] = 1.0f / sqrtf(sq * (1.0f / 384.f) + 1e-6f); stats[2 * row + 1] = 1.0f / sqrtf(skv * (1.0f / 256.f) + 1e-6f); }
.LBB0_461:
	v_mov_b32_e32 v34, s21
	v_mov_b32_e32 v35, s23
	v_pk_add_f32 v[34:35], s[36:37], v[34:35]
	v_mov_b32_e32 v32, s38
	v_add_f32_e32 v34, v34, v35
	v_fmamk_f32 v34, v34, 0x3b2aaaab, v84
	v_rsq_f32_e32 v144, v34
	v_mov_b32_e32 v33, s39
	v_pk_add_f32 v[32:33], s[16:17], v[32:33]
	v_add_f32_e32 v32, v32, v33
	v_mul_f32_e32 v32, 0.5, v32
	v_fmamk_f32 v32, v32, 0x3b800000, v84
	s_add_i32 s16, s20, 4
	s_ashr_i32 s17, s16, 31
	v_rsq_f32_e32 v145, v32
	s_lshl_b64 s[16:17], s[16:17], 2
	s_add_u32 s36, s1, s16
	s_addc_u32 s37, s3, s17
	v_mov_b32_e32 v32, v144
	v_mov_b32_e32 v33, v145
	global_store_dwordx2 v75, v[32:33], s[36:37]
	s_or_b64 exec, exec, s[34:35]
	s_and_saveexec_b64 s[16:17], s[8:9]
	s_cbranch_execz .LBB0_460

; __device__ __forceinline__ float wave_sum_fast(float x) { x = reduce16(x); return (rl_(x, 0) + rl_(x, 16)) + (rl_(x, 32) + rl_(x, 48)); }
; __device__ __forceinline__ void prep_even_phase(const Ctx& F) {
;     ...
;             sq = wave_sum_fast(sq); skv = wave_sum_fast(skv) * 0.5f;
;             if (lane == 0) { stats[2 * row] = 1.0f / sqrtf(sq * (1.0f / 384.f) + 1e-6f); stats[2 * row + 1] = 1.0f / sqrtf(skv * (1.0f / 256.f) + 1e-6f); }
.LBB0_531:
	v_mov_b32_e32 v18, s21
	v_mov_b32_e32 v19, s23
	v_pk_add_f32 v[18:19], s[34:35], v[18:19]
	v_mov_b32_e32 v16, s36
	v_add_f32_e32 v18, v18, v19
	v_fmamk_f32 v18, v18, 0x3b2aaaab, v84
	v_rsq_f32_e32 v146, v18
	v_mov_b32_e32 v17, s37
	v_pk_add_f32 v[16:17], s[16:17], v[16:17]
	v_add_f32_e32 v16, v16, v17
	v_mul_f32_e32 v16, 0.5, v16
	v_fmamk_f32 v16, v16, 0x3b800000, v84
	s_add_i32 s16, s20, 6
	s_ashr_i32 s17, s16, 31
	v_rsq_f32_e32 v147, v16
	s_lshl_b64 s[16:17], s[16:17], 2
	s_add_u32 s34, s1, s16
	s_addc_u32 s35, s3, s17
	v_mov_b32_e32 v16, v146
	v_mov_b32_e32 v17, v147
	global_store_dwordx2 v75, v[16:17], s[34:35]
	s_or_b64 exec, exec, s[30:31]
	s_and_saveexec_b64 s[16:17], s[8:9]
	s_cbranch_execz .LBB0_530
